# code placement: W2 K-loop body shifted by 40 bytes (nops outside the loop)
# speedup vs baseline: 1.0050x; 1.0050x over previous
.LBB0_1508:
	s_ashr_i32 s27, s26, 31
	s_lshl_b64 s[28:29], s[26:27], 21
	s_add_u32 s28, s10, s28
	s_addc_u32 s29, s11, s29
	s_and_b64 s[30:31], s[14:15], exec
	s_cselect_b32 s27, s29, s17
	s_cselect_b32 s55, s28, s16
	s_ashr_i32 s25, s24, 31
	s_lshl_b64 s[30:31], s[24:25], 21
	s_add_u32 s30, s38, s30
	s_addc_u32 s31, s39, s31
	s_and_b64 s[36:37], s[14:15], exec
	s_cselect_b32 s25, s31, s35
	s_cselect_b32 s56, s30, s34
	s_add_u32 s16, s16, 0x100080
	s_addc_u32 s17, s17, 0
	s_add_u32 s57, s34, 0x100
	v_mov_b32_e32 v2, 0
	s_addc_u32 s61, s35, 0
	s_mov_b32 s62, -2
	s_waitcnt lgkmcnt(0)
	v_mov_b32_e32 v3, v2
	v_mov_b32_e32 v4, v2
	v_mov_b32_e32 v5, v2
	v_mov_b32_e32 v6, v2
	v_mov_b32_e32 v7, v2
	v_mov_b32_e32 v8, v2
	v_mov_b32_e32 v9, v2
	v_mov_b32_e32 v18, v2
	v_mov_b32_e32 v19, v2
	v_mov_b32_e32 v20, v2
	v_mov_b32_e32 v21, v2
	v_mov_b32_e32 v22, v2
	v_mov_b32_e32 v23, v2
	v_mov_b32_e32 v24, v2
	v_mov_b32_e32 v25, v2
	v_mov_b32_e32 v34, v2
	v_mov_b32_e32 v35, v2
	v_mov_b32_e32 v36, v2
	v_mov_b32_e32 v37, v2
	v_mov_b32_e32 v38, v2
	v_mov_b32_e32 v39, v2
	v_mov_b32_e32 v40, v2
	v_mov_b32_e32 v41, v2
	v_mov_b32_e32 v66, v2
	v_mov_b32_e32 v67, v2
	v_mov_b32_e32 v68, v2
	v_mov_b32_e32 v69, v2
	v_mov_b32_e32 v70, v2
	v_mov_b32_e32 v71, v2
	v_mov_b32_e32 v72, v2
	v_mov_b32_e32 v73, v2
	v_mov_b32_e32 v10, v2
	v_mov_b32_e32 v11, v2
	v_mov_b32_e32 v12, v2
	v_mov_b32_e32 v13, v2
	v_mov_b32_e32 v14, v2
	v_mov_b32_e32 v15, v2
	v_mov_b32_e32 v16, v2
	v_mov_b32_e32 v17, v2
	v_mov_b32_e32 v26, v2
	v_mov_b32_e32 v27, v2
	v_mov_b32_e32 v28, v2
	v_mov_b32_e32 v29, v2
	v_mov_b32_e32 v30, v2
	v_mov_b32_e32 v31, v2
	v_mov_b32_e32 v32, v2
	v_mov_b32_e32 v33, v2
	v_mov_b32_e32 v58, v2
	v_mov_b32_e32 v59, v2
	v_mov_b32_e32 v60, v2
	v_mov_b32_e32 v61, v2
	v_mov_b32_e32 v62, v2
	v_mov_b32_e32 v63, v2
	v_mov_b32_e32 v64, v2
	v_mov_b32_e32 v65, v2
	v_mov_b32_e32 v74, v2
	v_mov_b32_e32 v75, v2
	v_mov_b32_e32 v76, v2
	v_mov_b32_e32 v77, v2
	v_mov_b32_e32 v78, v2
	v_mov_b32_e32 v79, v2
	v_mov_b32_e32 v80, v2
	v_mov_b32_e32 v81, v2
	v_mov_b32_e32 v82, v2
	v_mov_b32_e32 v83, v2
	v_mov_b32_e32 v84, v2
	v_mov_b32_e32 v85, v2
	v_mov_b32_e32 v86, v2
	v_mov_b32_e32 v87, v2
	v_mov_b32_e32 v88, v2
	v_mov_b32_e32 v89, v2
	v_mov_b32_e32 v98, v2
	v_mov_b32_e32 v99, v2
	v_mov_b32_e32 v100, v2
	v_mov_b32_e32 v101, v2
	v_mov_b32_e32 v102, v2
	v_mov_b32_e32 v103, v2
	v_mov_b32_e32 v104, v2
	v_mov_b32_e32 v105, v2
	v_mov_b32_e32 v114, v2
	v_mov_b32_e32 v115, v2
	v_mov_b32_e32 v116, v2
	v_mov_b32_e32 v117, v2
	v_mov_b32_e32 v118, v2
	v_mov_b32_e32 v119, v2
	v_mov_b32_e32 v120, v2
	v_mov_b32_e32 v121, v2
	v_mov_b32_e32 v130, v2
	v_mov_b32_e32 v131, v2
	v_mov_b32_e32 v132, v2
	v_mov_b32_e32 v133, v2
	v_mov_b32_e32 v134, v2
	v_mov_b32_e32 v135, v2
	v_mov_b32_e32 v136, v2
	v_mov_b32_e32 v137, v2
	v_mov_b32_e32 v90, v2
	v_mov_b32_e32 v91, v2
	v_mov_b32_e32 v92, v2
	v_mov_b32_e32 v93, v2
	v_mov_b32_e32 v94, v2
	v_mov_b32_e32 v95, v2
	v_mov_b32_e32 v96, v2
	v_mov_b32_e32 v97, v2
	v_mov_b32_e32 v106, v2
	v_mov_b32_e32 v107, v2
	v_mov_b32_e32 v108, v2
	v_mov_b32_e32 v109, v2
	v_mov_b32_e32 v110, v2
	v_mov_b32_e32 v111, v2
	v_mov_b32_e32 v112, v2
	v_mov_b32_e32 v113, v2
	v_mov_b32_e32 v122, v2
	v_mov_b32_e32 v123, v2
	v_mov_b32_e32 v124, v2
	v_mov_b32_e32 v125, v2
	v_mov_b32_e32 v126, v2
	v_mov_b32_e32 v127, v2
	v_mov_b32_e32 v128, v2
	v_mov_b32_e32 v129, v2
	v_mov_b32_e32 v138, v2
	v_mov_b32_e32 v139, v2
	v_mov_b32_e32 v140, v2
	v_mov_b32_e32 v141, v2
	v_mov_b32_e32 v142, v2
	v_mov_b32_e32 v143, v2
	v_mov_b32_e32 v144, v2
	v_mov_b32_e32 v145, v2
	s_nop 0
	s_nop 0
	s_nop 0
	s_nop 0
	s_nop 0
	s_nop 0
	s_nop 0
	s_nop 0
	s_nop 0
	s_nop 0
.LBB0_1509:
	s_add_u32 s34, s16, 0xfff00080
	s_addc_u32 s35, s17, -1
	s_add_i32 s63, 0, 0x10000
	s_cmp_eq_u32 s62, 60
	s_cselect_b32 s37, s27, s35
	s_cselect_b32 s36, s55, s34
	s_cselect_b32 s35, s25, s61
	s_cselect_b32 s34, s56, s57
	s_add_i32 s70, 0, 0x14000
	v_add_u32_e32 v54, s63, v195
	v_add_u32_e32 v180, s70, v195
	ds_read_b128 v[42:45], v54
	ds_read_b128 v[46:49], v54 offset:1024
	ds_read_b128 v[50:53], v54 offset:2048
	ds_read_b128 v[54:57], v54 offset:3072
	ds_read_b128 v[168:171], v180
	ds_read_b128 v[172:175], v180 offset:1024
	ds_read_b128 v[176:179], v180 offset:2048
	ds_read_b128 v[180:183], v180 offset:3072
	v_lshl_add_u64 v[192:193], s[16:17], 0, v[152:153]
	s_add_i32 m0, s41, 0xc000
	ds_read_b128 v[184:187], v197
	ds_read_b128 v[188:191], v197 offset:1024
	ds_read_b128 v[210:213], v197 offset:2048
	ds_read_b128 v[214:217], v197 offset:3072
	ds_read_b128 v[218:221], v197 offset:4096
	ds_read_b128 v[222:225], v197 offset:5120
	ds_read_b128 v[226:229], v197 offset:6144
	ds_read_b128 v[230:233], v197 offset:7168
	global_load_lds_dwordx4 v[192:193], off
	v_lshl_add_u64 v[192:193], s[16:17], 0, v[166:167]
	s_add_i32 m0, s41, 0xe000
	s_nop 0
	global_load_lds_dwordx4 v[192:193], off
	s_waitcnt vmcnt(8)
	s_waitcnt lgkmcnt(0)
	s_barrier
	s_setprio 1
	s_waitcnt lgkmcnt(0)
	v_mfma_f32_16x16x32_bf16 v[142:145], v[42:45], v[184:187], v[142:145]
	v_mfma_f32_16x16x32_bf16 v[138:141], v[50:53], v[184:187], v[138:141]
	v_mfma_f32_16x16x32_bf16 v[126:129], v[42:45], v[210:213], v[126:129]
	v_mfma_f32_16x16x32_bf16 v[122:125], v[50:53], v[210:213], v[122:125]
	v_mfma_f32_16x16x32_bf16 v[110:113], v[42:45], v[218:221], v[110:113]
	v_mfma_f32_16x16x32_bf16 v[106:109], v[50:53], v[218:221], v[106:109]
	v_mfma_f32_16x16x32_bf16 v[94:97], v[42:45], v[226:229], v[94:97]
	v_mfma_f32_16x16x32_bf16 v[90:93], v[50:53], v[226:229], v[90:93]
	v_mfma_f32_16x16x32_bf16 v[142:145], v[46:49], v[188:191], v[142:145]
	v_mfma_f32_16x16x32_bf16 v[138:141], v[54:57], v[188:191], v[138:141]
	v_mfma_f32_16x16x32_bf16 v[126:129], v[46:49], v[214:217], v[126:129]
	v_mfma_f32_16x16x32_bf16 v[122:125], v[54:57], v[214:217], v[122:125]
	v_mfma_f32_16x16x32_bf16 v[110:113], v[46:49], v[222:225], v[110:113]
	v_mfma_f32_16x16x32_bf16 v[106:109], v[54:57], v[222:225], v[106:109]
	v_mfma_f32_16x16x32_bf16 v[94:97], v[46:49], v[230:233], v[94:97]
	v_mfma_f32_16x16x32_bf16 v[90:93], v[54:57], v[230:233], v[90:93]
	s_setprio 0
	s_setprio 1
	v_mfma_f32_16x16x32_bf16 v[134:137], v[168:171], v[184:187], v[134:137]
	v_mfma_f32_16x16x32_bf16 v[130:133], v[176:179], v[184:187], v[130:133]
	v_mfma_f32_16x16x32_bf16 v[118:121], v[168:171], v[210:213], v[118:121]
	v_mfma_f32_16x16x32_bf16 v[114:117], v[176:179], v[210:213], v[114:117]
	v_mfma_f32_16x16x32_bf16 v[102:105], v[168:171], v[218:221], v[102:105]
	v_mfma_f32_16x16x32_bf16 v[98:101], v[176:179], v[218:221], v[98:101]
	v_mfma_f32_16x16x32_bf16 v[86:89], v[168:171], v[226:229], v[86:89]
	v_mfma_f32_16x16x32_bf16 v[82:85], v[176:179], v[226:229], v[82:85]
	v_mfma_f32_16x16x32_bf16 v[134:137], v[172:175], v[188:191], v[134:137]
	v_mfma_f32_16x16x32_bf16 v[130:133], v[180:183], v[188:191], v[130:133]
	v_mfma_f32_16x16x32_bf16 v[118:121], v[172:175], v[214:217], v[118:121]
	v_mfma_f32_16x16x32_bf16 v[114:117], v[180:183], v[214:217], v[114:117]
	v_mfma_f32_16x16x32_bf16 v[102:105], v[172:175], v[222:225], v[102:105]
	v_mfma_f32_16x16x32_bf16 v[98:101], v[180:183], v[222:225], v[98:101]
	v_mfma_f32_16x16x32_bf16 v[86:89], v[172:175], v[230:233], v[86:89]
	v_mfma_f32_16x16x32_bf16 v[82:85], v[180:183], v[230:233], v[82:85]
	s_setprio 0
	s_barrier
	s_add_i32 s63, s63, s40
	v_lshl_add_u64 v[192:193], s[34:35], 0, v[0:1]
	s_mov_b32 m0, s63
	ds_read_b128 v[184:187], v197 offset:16384
	ds_read_b128 v[188:191], v197 offset:17408
	ds_read_b128 v[210:213], v197 offset:18432
	ds_read_b128 v[214:217], v197 offset:19456
	ds_read_b128 v[218:221], v197 offset:20480
	ds_read_b128 v[222:225], v197 offset:21504
	ds_read_b128 v[226:229], v197 offset:22528
	ds_read_b128 v[230:233], v197 offset:23552
	global_load_lds_dwordx4 v[192:193], off
	s_add_i32 m0, s63, 0x2000
	s_add_u32 s66, s34, 0x100000
	v_lshl_add_u64 v[234:235], s[34:35], 0, v[146:147]
	s_addc_u32 s67, s35, 0
	s_add_i32 s63, s70, s40
	global_load_lds_dwordx4 v[234:235], off
	v_lshl_add_u64 v[236:237], s[66:67], 0, v[0:1]
	s_mov_b32 m0, s63
	v_lshl_add_u64 v[238:239], s[36:37], 0, v[148:149]
	global_load_lds_dwordx4 v[236:237], off
	v_lshl_add_u64 v[236:237], s[66:67], 0, v[146:147]
	s_add_i32 m0, s63, 0x2000
	s_nop 0
	global_load_lds_dwordx4 v[236:237], off
	v_lshl_add_u64 v[236:237], s[36:37], 0, v[150:151]
	s_mov_b32 m0, s41
	s_nop 0
	global_load_lds_dwordx4 v[236:237], off
	s_mov_b32 m0, s42
	s_nop 0
	global_load_lds_dwordx4 v[238:239], off
	s_waitcnt vmcnt(8)
	s_waitcnt lgkmcnt(0)
	s_barrier
	s_setprio 1
	s_waitcnt lgkmcnt(0)
	v_mfma_f32_16x16x32_bf16 v[78:81], v[42:45], v[184:187], v[78:81]
	v_mfma_f32_16x16x32_bf16 v[74:77], v[50:53], v[184:187], v[74:77]
	v_mfma_f32_16x16x32_bf16 v[62:65], v[42:45], v[210:213], v[62:65]
	v_mfma_f32_16x16x32_bf16 v[58:61], v[50:53], v[210:213], v[58:61]
	v_mfma_f32_16x16x32_bf16 v[30:33], v[42:45], v[218:221], v[30:33]
	v_mfma_f32_16x16x32_bf16 v[26:29], v[50:53], v[218:221], v[26:29]
	v_mfma_f32_16x16x32_bf16 v[14:17], v[42:45], v[226:229], v[14:17]
	v_mfma_f32_16x16x32_bf16 v[10:13], v[50:53], v[226:229], v[10:13]
	v_mfma_f32_16x16x32_bf16 v[78:81], v[46:49], v[188:191], v[78:81]
	v_mfma_f32_16x16x32_bf16 v[74:77], v[54:57], v[188:191], v[74:77]
	v_mfma_f32_16x16x32_bf16 v[62:65], v[46:49], v[214:217], v[62:65]
	v_mfma_f32_16x16x32_bf16 v[58:61], v[54:57], v[214:217], v[58:61]
	v_mfma_f32_16x16x32_bf16 v[30:33], v[46:49], v[222:225], v[30:33]
	v_mfma_f32_16x16x32_bf16 v[26:29], v[54:57], v[222:225], v[26:29]
	v_mfma_f32_16x16x32_bf16 v[14:17], v[46:49], v[230:233], v[14:17]
	v_mfma_f32_16x16x32_bf16 v[10:13], v[54:57], v[230:233], v[10:13]
	s_setprio 0
	s_setprio 1
	v_mfma_f32_16x16x32_bf16 v[38:41], v[168:171], v[210:213], v[38:41]
	v_mfma_f32_16x16x32_bf16 v[34:37], v[176:179], v[210:213], v[34:37]
	v_mfma_f32_16x16x32_bf16 v[22:25], v[168:171], v[218:221], v[22:25]
	v_mfma_f32_16x16x32_bf16 v[18:21], v[176:179], v[218:221], v[18:21]
	v_mfma_f32_16x16x32_bf16 v[6:9], v[168:171], v[226:229], v[6:9]
	v_mfma_f32_16x16x32_bf16 v[2:5], v[176:179], v[226:229], v[2:5]
	v_mfma_f32_16x16x32_bf16 v[42:45], v[168:171], v[184:187], v[70:73]
	v_mfma_f32_16x16x32_bf16 v[46:49], v[176:179], v[184:187], v[66:69]
	v_mfma_f32_16x16x32_bf16 v[38:41], v[172:175], v[214:217], v[38:41]
	v_mfma_f32_16x16x32_bf16 v[34:37], v[180:183], v[214:217], v[34:37]
	v_mfma_f32_16x16x32_bf16 v[22:25], v[172:175], v[222:225], v[22:25]
	v_mfma_f32_16x16x32_bf16 v[18:21], v[180:183], v[222:225], v[18:21]
	v_mfma_f32_16x16x32_bf16 v[6:9], v[172:175], v[230:233], v[6:9]
	v_mfma_f32_16x16x32_bf16 v[2:5], v[180:183], v[230:233], v[2:5]
	v_mfma_f32_16x16x32_bf16 v[42:45], v[172:175], v[188:191], v[42:45]
	v_mfma_f32_16x16x32_bf16 v[46:49], v[180:183], v[188:191], v[46:49]
	s_setprio 0
	s_barrier
	s_add_i32 s63, 0, 0x18000
	s_add_i32 s66, 0, 0x1c000
	v_add_u32_e32 v70, s63, v195
	v_add_u32_e32 v180, s66, v195
	ds_read_b128 v[50:53], v70
	ds_read_b128 v[54:57], v70 offset:1024
	ds_read_b128 v[66:69], v70 offset:2048
	ds_read_b128 v[70:73], v70 offset:3072
	ds_read_b128 v[168:171], v180
	ds_read_b128 v[172:175], v180 offset:1024
	ds_read_b128 v[176:179], v180 offset:2048
	ds_read_b128 v[180:183], v180 offset:3072
	s_add_u32 s36, s36, 0x100000
	s_addc_u32 s37, s37, 0
	s_mov_b32 m0, s43
	v_lshl_add_u64 v[240:241], s[36:37], 0, v[150:151]
	ds_read_b128 v[184:187], v197 offset:32768
	ds_read_b128 v[188:191], v197 offset:33792
	ds_read_b128 v[210:213], v197 offset:34816
	ds_read_b128 v[214:217], v197 offset:35840
	ds_read_b128 v[218:221], v197 offset:36864
	ds_read_b128 v[222:225], v197 offset:37888
	ds_read_b128 v[226:229], v197 offset:38912
	ds_read_b128 v[230:233], v197 offset:39936
	global_load_lds_dwordx4 v[240:241], off
	v_lshl_add_u64 v[240:241], s[36:37], 0, v[148:149]
	s_mov_b32 m0, s44
	s_nop 0
	global_load_lds_dwordx4 v[240:241], off
	s_waitcnt vmcnt(8)
	s_waitcnt lgkmcnt(0)
	s_barrier
	s_setprio 1
	s_waitcnt lgkmcnt(0)
	v_mfma_f32_16x16x32_bf16 v[142:145], v[50:53], v[184:187], v[142:145]
	v_mfma_f32_16x16x32_bf16 v[138:141], v[66:69], v[184:187], v[138:141]
	v_mfma_f32_16x16x32_bf16 v[126:129], v[50:53], v[210:213], v[126:129]
	v_mfma_f32_16x16x32_bf16 v[122:125], v[66:69], v[210:213], v[122:125]
	v_mfma_f32_16x16x32_bf16 v[110:113], v[50:53], v[218:221], v[110:113]
	v_mfma_f32_16x16x32_bf16 v[106:109], v[66:69], v[218:221], v[106:109]
	v_mfma_f32_16x16x32_bf16 v[94:97], v[50:53], v[226:229], v[94:97]
	v_mfma_f32_16x16x32_bf16 v[90:93], v[66:69], v[226:229], v[90:93]
	v_mfma_f32_16x16x32_bf16 v[142:145], v[54:57], v[188:191], v[142:145]
	v_mfma_f32_16x16x32_bf16 v[138:141], v[70:73], v[188:191], v[138:141]
	v_mfma_f32_16x16x32_bf16 v[126:129], v[54:57], v[214:217], v[126:129]
	v_mfma_f32_16x16x32_bf16 v[122:125], v[70:73], v[214:217], v[122:125]
	v_mfma_f32_16x16x32_bf16 v[110:113], v[54:57], v[222:225], v[110:113]
	v_mfma_f32_16x16x32_bf16 v[106:109], v[70:73], v[222:225], v[106:109]
	v_mfma_f32_16x16x32_bf16 v[94:97], v[54:57], v[230:233], v[94:97]
	v_mfma_f32_16x16x32_bf16 v[90:93], v[70:73], v[230:233], v[90:93]
	s_setprio 0
	s_setprio 1
	v_mfma_f32_16x16x32_bf16 v[134:137], v[168:171], v[184:187], v[134:137]
	v_mfma_f32_16x16x32_bf16 v[130:133], v[176:179], v[184:187], v[130:133]
	v_mfma_f32_16x16x32_bf16 v[118:121], v[168:171], v[210:213], v[118:121]
	v_mfma_f32_16x16x32_bf16 v[114:117], v[176:179], v[210:213], v[114:117]
	v_mfma_f32_16x16x32_bf16 v[102:105], v[168:171], v[218:221], v[102:105]
	v_mfma_f32_16x16x32_bf16 v[98:101], v[176:179], v[218:221], v[98:101]
	v_mfma_f32_16x16x32_bf16 v[86:89], v[168:171], v[226:229], v[86:89]
	v_mfma_f32_16x16x32_bf16 v[82:85], v[176:179], v[226:229], v[82:85]
	v_mfma_f32_16x16x32_bf16 v[134:137], v[172:175], v[188:191], v[134:137]
	v_mfma_f32_16x16x32_bf16 v[130:133], v[180:183], v[188:191], v[130:133]
	v_mfma_f32_16x16x32_bf16 v[118:121], v[172:175], v[214:217], v[118:121]
	v_mfma_f32_16x16x32_bf16 v[114:117], v[180:183], v[214:217], v[114:117]
	v_mfma_f32_16x16x32_bf16 v[102:105], v[172:175], v[222:225], v[102:105]
	v_mfma_f32_16x16x32_bf16 v[98:101], v[180:183], v[222:225], v[98:101]
	v_mfma_f32_16x16x32_bf16 v[86:89], v[172:175], v[230:233], v[86:89]
	v_mfma_f32_16x16x32_bf16 v[82:85], v[180:183], v[230:233], v[82:85]
	s_setprio 0
	s_barrier
	s_add_i32 s36, s63, s40
	v_lshl_add_u64 v[192:193], v[192:193], 0, s[6:7]
	s_mov_b32 m0, s36
	ds_read_b128 v[184:187], v197 offset:49152
	ds_read_b128 v[188:191], v197 offset:50176
	ds_read_b128 v[210:213], v197 offset:51200
	ds_read_b128 v[214:217], v197 offset:52224
	ds_read_b128 v[218:221], v197 offset:53248
	ds_read_b128 v[222:225], v197 offset:54272
	ds_read_b128 v[226:229], v197 offset:55296
	ds_read_b128 v[230:233], v197 offset:56320
	global_load_lds_dwordx4 v[192:193], off
	s_add_i32 m0, s36, 0x2000
	s_add_u32 s34, s34, 0x100080
	v_lshl_add_u64 v[192:193], v[234:235], 0, s[6:7]
	s_addc_u32 s35, s35, 0
	s_add_i32 s36, s66, s40
	global_load_lds_dwordx4 v[192:193], off
	v_lshl_add_u64 v[192:193], s[34:35], 0, v[0:1]
	s_mov_b32 m0, s36
	s_nop 0
	global_load_lds_dwordx4 v[192:193], off
	v_lshl_add_u64 v[192:193], s[34:35], 0, v[146:147]
	s_add_i32 m0, s36, 0x2000
	s_nop 0
	global_load_lds_dwordx4 v[192:193], off
	v_lshl_add_u64 v[192:193], v[236:237], 0, s[6:7]
	s_mov_b32 m0, s52
	s_nop 0
	global_load_lds_dwordx4 v[192:193], off
	v_lshl_add_u64 v[192:193], v[238:239], 0, s[6:7]
	s_mov_b32 m0, s53
	s_nop 0
	global_load_lds_dwordx4 v[192:193], off
	s_waitcnt vmcnt(8)
	s_waitcnt lgkmcnt(0)
	s_barrier
	s_setprio 1
	s_waitcnt lgkmcnt(0)
	v_mfma_f32_16x16x32_bf16 v[78:81], v[50:53], v[184:187], v[78:81]
	v_mfma_f32_16x16x32_bf16 v[74:77], v[66:69], v[184:187], v[74:77]
	v_mfma_f32_16x16x32_bf16 v[62:65], v[50:53], v[210:213], v[62:65]
	v_mfma_f32_16x16x32_bf16 v[58:61], v[66:69], v[210:213], v[58:61]
	v_mfma_f32_16x16x32_bf16 v[30:33], v[50:53], v[218:221], v[30:33]
	v_mfma_f32_16x16x32_bf16 v[26:29], v[66:69], v[218:221], v[26:29]
	v_mfma_f32_16x16x32_bf16 v[14:17], v[50:53], v[226:229], v[14:17]
	v_mfma_f32_16x16x32_bf16 v[10:13], v[66:69], v[226:229], v[10:13]
	v_mfma_f32_16x16x32_bf16 v[78:81], v[54:57], v[188:191], v[78:81]
	v_mfma_f32_16x16x32_bf16 v[74:77], v[70:73], v[188:191], v[74:77]
	v_mfma_f32_16x16x32_bf16 v[62:65], v[54:57], v[214:217], v[62:65]
	v_mfma_f32_16x16x32_bf16 v[58:61], v[70:73], v[214:217], v[58:61]
	v_mfma_f32_16x16x32_bf16 v[30:33], v[54:57], v[222:225], v[30:33]
	v_mfma_f32_16x16x32_bf16 v[26:29], v[70:73], v[222:225], v[26:29]
	v_mfma_f32_16x16x32_bf16 v[14:17], v[54:57], v[230:233], v[14:17]
	v_mfma_f32_16x16x32_bf16 v[10:13], v[70:73], v[230:233], v[10:13]
	s_setprio 0
	s_setprio 1
	v_mfma_f32_16x16x32_bf16 v[42:45], v[168:171], v[184:187], v[42:45]
	v_mfma_f32_16x16x32_bf16 v[70:73], v[172:175], v[188:191], v[42:45]
	v_mfma_f32_16x16x32_bf16 v[42:45], v[176:179], v[184:187], v[46:49]
	v_mfma_f32_16x16x32_bf16 v[38:41], v[168:171], v[210:213], v[38:41]
	v_mfma_f32_16x16x32_bf16 v[34:37], v[176:179], v[210:213], v[34:37]
	v_mfma_f32_16x16x32_bf16 v[22:25], v[168:171], v[218:221], v[22:25]
	v_mfma_f32_16x16x32_bf16 v[18:21], v[176:179], v[218:221], v[18:21]
	v_mfma_f32_16x16x32_bf16 v[6:9], v[168:171], v[226:229], v[6:9]
	v_mfma_f32_16x16x32_bf16 v[2:5], v[176:179], v[226:229], v[2:5]
	v_mfma_f32_16x16x32_bf16 v[66:69], v[180:183], v[188:191], v[42:45]
	v_mfma_f32_16x16x32_bf16 v[38:41], v[172:175], v[214:217], v[38:41]
	v_mfma_f32_16x16x32_bf16 v[34:37], v[180:183], v[214:217], v[34:37]
	v_mfma_f32_16x16x32_bf16 v[22:25], v[172:175], v[222:225], v[22:25]
	v_mfma_f32_16x16x32_bf16 v[18:21], v[180:183], v[222:225], v[18:21]
	v_mfma_f32_16x16x32_bf16 v[6:9], v[172:175], v[230:233], v[6:9]
	v_mfma_f32_16x16x32_bf16 v[2:5], v[180:183], v[230:233], v[2:5]
	s_setprio 0
	s_barrier
	s_add_i32 s62, s62, 2
	s_add_u32 s16, s16, 0x100
	s_addc_u32 s17, s17, 0
	s_add_u32 s57, s57, 0x100
	s_addc_u32 s61, s61, 0
	s_cmp_gt_u32 s62, 61
	s_cbranch_scc0 .LBB0_1509
	s_nop 0
	s_nop 0
	s_nop 0
	s_nop 0
	s_nop 0
	s_nop 0
	s_and_b64 vcc, exec, s[22:23]
	s_cbranch_vccz .LBB0_1512
	s_barrier
